# P0 mod GEMV: 64 weight loads per item issued up front, k loop unrolled (on top of 8-group P7 stagger)
# speedup vs baseline: 1.0035x; 1.0035x over previous
.LBB0_384:
	s_or_b64 exec, exec, s[0:1]
	s_mul_i32 s5, s5, 24
	v_readlane_b32 s64, v252, 33
	s_sub_i32 s0, s6, s5
	v_readlane_b32 s66, v252, 35
	v_readlane_b32 s67, v252, 36
	v_lshl_or_b32 v86, s0, 8, v106
	v_add_u32_e32 v0, s4, v107
	v_mov_b64_e32 v[2:3], s[66:67]
	s_movk_i32 s5, 0x6000
	v_mad_i64_i32 v[2:3], s[0:1], v0, s5, v[2:3]
	v_ashrrev_i32_e32 v87, 31, v86
	s_waitcnt vmcnt(16)
	v_mov_b32_e32 v94, 0
	v_lshl_add_u64 v[96:97], v[86:87], 2, v[2:3]
	s_mov_b64 s[0:1], 0
	v_mov_b32_e32 v111, v108
	v_mov_b32_e32 v95, v94
	v_mov_b32_e32 v92, v94
	v_mov_b32_e32 v93, v94
	v_mov_b32_e32 v90, v94
	v_mov_b32_e32 v91, v94
	v_mov_b32_e32 v88, v94
	v_mov_b32_e32 v89, v94
	v_mov_b32_e32 v0, v94
	s_mov_b32 s7, 0xc000
	s_waitcnt lgkmcnt(0)
	s_barrier
	v_readlane_b32 s65, v252, 34
	v_readlane_b32 s68, v252, 37
	v_readlane_b32 s69, v252, 38
	v_readlane_b32 s70, v252, 39
	v_readlane_b32 s71, v252, 40
	v_readlane_b32 s72, v252, 41
	v_readlane_b32 s73, v252, 42
	v_readlane_b32 s74, v252, 43
	v_readlane_b32 s75, v252, 44
	v_readlane_b32 s76, v252, 45
	v_readlane_b32 s77, v252, 46
	v_readlane_b32 s78, v252, 47
	v_readlane_b32 s79, v252, 48
	s_waitcnt vmcnt(7)
	v_mov_b32_e32 v198, v96
	v_mov_b32_e32 v199, v97
	global_load_dword v134, v[198:199], off
	v_add_co_u32_e32 v198, vcc, s5, v198
	s_nop 0
	v_addc_co_u32_e32 v199, vcc, 0, v199, vcc
	global_load_dword v135, v[198:199], off
	v_add_co_u32_e32 v198, vcc, s5, v198
	s_nop 0
	v_addc_co_u32_e32 v199, vcc, 0, v199, vcc
	global_load_dword v136, v[198:199], off
	v_add_co_u32_e32 v198, vcc, s5, v198
	s_nop 0
	v_addc_co_u32_e32 v199, vcc, 0, v199, vcc
	global_load_dword v137, v[198:199], off
	v_add_co_u32_e32 v198, vcc, s5, v198
	s_nop 0
	v_addc_co_u32_e32 v199, vcc, 0, v199, vcc
	global_load_dword v138, v[198:199], off
	v_add_co_u32_e32 v198, vcc, s5, v198
	s_nop 0
	v_addc_co_u32_e32 v199, vcc, 0, v199, vcc
	global_load_dword v139, v[198:199], off
	v_add_co_u32_e32 v198, vcc, s5, v198
	s_nop 0
	v_addc_co_u32_e32 v199, vcc, 0, v199, vcc
	global_load_dword v140, v[198:199], off
	v_add_co_u32_e32 v198, vcc, s5, v198
	s_nop 0
	v_addc_co_u32_e32 v199, vcc, 0, v199, vcc
	global_load_dword v141, v[198:199], off
	v_add_co_u32_e32 v198, vcc, s5, v198
	s_nop 0
	v_addc_co_u32_e32 v199, vcc, 0, v199, vcc
	global_load_dword v142, v[198:199], off
	v_add_co_u32_e32 v198, vcc, s5, v198
	s_nop 0
	v_addc_co_u32_e32 v199, vcc, 0, v199, vcc
	global_load_dword v143, v[198:199], off
	v_add_co_u32_e32 v198, vcc, s5, v198
	s_nop 0
	v_addc_co_u32_e32 v199, vcc, 0, v199, vcc
	global_load_dword v144, v[198:199], off
	v_add_co_u32_e32 v198, vcc, s5, v198
	s_nop 0
	v_addc_co_u32_e32 v199, vcc, 0, v199, vcc
	global_load_dword v145, v[198:199], off
	v_add_co_u32_e32 v198, vcc, s5, v198
	s_nop 0
	v_addc_co_u32_e32 v199, vcc, 0, v199, vcc
	global_load_dword v146, v[198:199], off
	v_add_co_u32_e32 v198, vcc, s5, v198
	s_nop 0
	v_addc_co_u32_e32 v199, vcc, 0, v199, vcc
	global_load_dword v147, v[198:199], off
	v_add_co_u32_e32 v198, vcc, s5, v198
	s_nop 0
	v_addc_co_u32_e32 v199, vcc, 0, v199, vcc
	global_load_dword v148, v[198:199], off
	v_add_co_u32_e32 v198, vcc, s5, v198
	s_nop 0
	v_addc_co_u32_e32 v199, vcc, 0, v199, vcc
	global_load_dword v149, v[198:199], off
	v_add_co_u32_e32 v198, vcc, s5, v198
	s_nop 0
	v_addc_co_u32_e32 v199, vcc, 0, v199, vcc
	global_load_dword v150, v[198:199], off
	v_add_co_u32_e32 v198, vcc, s5, v198
	s_nop 0
	v_addc_co_u32_e32 v199, vcc, 0, v199, vcc
	global_load_dword v151, v[198:199], off
	v_add_co_u32_e32 v198, vcc, s5, v198
	s_nop 0
	v_addc_co_u32_e32 v199, vcc, 0, v199, vcc
	global_load_dword v152, v[198:199], off
	v_add_co_u32_e32 v198, vcc, s5, v198
	s_nop 0
	v_addc_co_u32_e32 v199, vcc, 0, v199, vcc
	global_load_dword v153, v[198:199], off
	v_add_co_u32_e32 v198, vcc, s5, v198
	s_nop 0
	v_addc_co_u32_e32 v199, vcc, 0, v199, vcc
	global_load_dword v154, v[198:199], off
	v_add_co_u32_e32 v198, vcc, s5, v198
	s_nop 0
	v_addc_co_u32_e32 v199, vcc, 0, v199, vcc
	global_load_dword v155, v[198:199], off
	v_add_co_u32_e32 v198, vcc, s5, v198
	s_nop 0
	v_addc_co_u32_e32 v199, vcc, 0, v199, vcc
	global_load_dword v156, v[198:199], off
	v_add_co_u32_e32 v198, vcc, s5, v198
	s_nop 0
	v_addc_co_u32_e32 v199, vcc, 0, v199, vcc
	global_load_dword v157, v[198:199], off
	v_add_co_u32_e32 v198, vcc, s5, v198
	s_nop 0
	v_addc_co_u32_e32 v199, vcc, 0, v199, vcc
	global_load_dword v158, v[198:199], off
	v_add_co_u32_e32 v198, vcc, s5, v198
	s_nop 0
	v_addc_co_u32_e32 v199, vcc, 0, v199, vcc
	global_load_dword v159, v[198:199], off
	v_add_co_u32_e32 v198, vcc, s5, v198
	s_nop 0
	v_addc_co_u32_e32 v199, vcc, 0, v199, vcc
	global_load_dword v160, v[198:199], off
	v_add_co_u32_e32 v198, vcc, s5, v198
	s_nop 0
	v_addc_co_u32_e32 v199, vcc, 0, v199, vcc
	global_load_dword v161, v[198:199], off
	v_add_co_u32_e32 v198, vcc, s5, v198
	s_nop 0
	v_addc_co_u32_e32 v199, vcc, 0, v199, vcc
	global_load_dword v162, v[198:199], off
	v_add_co_u32_e32 v198, vcc, s5, v198
	s_nop 0
	v_addc_co_u32_e32 v199, vcc, 0, v199, vcc
	global_load_dword v163, v[198:199], off
	v_add_co_u32_e32 v198, vcc, s5, v198
	s_nop 0
	v_addc_co_u32_e32 v199, vcc, 0, v199, vcc
	global_load_dword v164, v[198:199], off
	v_add_co_u32_e32 v198, vcc, s5, v198
	s_nop 0
	v_addc_co_u32_e32 v199, vcc, 0, v199, vcc
	global_load_dword v165, v[198:199], off
	v_add_co_u32_e32 v198, vcc, s5, v198
	s_nop 0
	v_addc_co_u32_e32 v199, vcc, 0, v199, vcc
	global_load_dword v166, v[198:199], off
	v_add_co_u32_e32 v198, vcc, s5, v198
	s_nop 0
	v_addc_co_u32_e32 v199, vcc, 0, v199, vcc
	global_load_dword v167, v[198:199], off
	v_add_co_u32_e32 v198, vcc, s5, v198
	s_nop 0
	v_addc_co_u32_e32 v199, vcc, 0, v199, vcc
	global_load_dword v168, v[198:199], off
	v_add_co_u32_e32 v198, vcc, s5, v198
	s_nop 0
	v_addc_co_u32_e32 v199, vcc, 0, v199, vcc
	global_load_dword v169, v[198:199], off
	v_add_co_u32_e32 v198, vcc, s5, v198
	s_nop 0
	v_addc_co_u32_e32 v199, vcc, 0, v199, vcc
	global_load_dword v170, v[198:199], off
	v_add_co_u32_e32 v198, vcc, s5, v198
	s_nop 0
	v_addc_co_u32_e32 v199, vcc, 0, v199, vcc
	global_load_dword v171, v[198:199], off
	v_add_co_u32_e32 v198, vcc, s5, v198
	s_nop 0
	v_addc_co_u32_e32 v199, vcc, 0, v199, vcc
	global_load_dword v172, v[198:199], off
	v_add_co_u32_e32 v198, vcc, s5, v198
	s_nop 0
	v_addc_co_u32_e32 v199, vcc, 0, v199, vcc
	global_load_dword v173, v[198:199], off
	v_add_co_u32_e32 v198, vcc, s5, v198
	s_nop 0
	v_addc_co_u32_e32 v199, vcc, 0, v199, vcc
	global_load_dword v174, v[198:199], off
	v_add_co_u32_e32 v198, vcc, s5, v198
	s_nop 0
	v_addc_co_u32_e32 v199, vcc, 0, v199, vcc
	global_load_dword v175, v[198:199], off
	v_add_co_u32_e32 v198, vcc, s5, v198
	s_nop 0
	v_addc_co_u32_e32 v199, vcc, 0, v199, vcc
	global_load_dword v176, v[198:199], off
	v_add_co_u32_e32 v198, vcc, s5, v198
	s_nop 0
	v_addc_co_u32_e32 v199, vcc, 0, v199, vcc
	global_load_dword v177, v[198:199], off
	v_add_co_u32_e32 v198, vcc, s5, v198
	s_nop 0
	v_addc_co_u32_e32 v199, vcc, 0, v199, vcc
	global_load_dword v178, v[198:199], off
	v_add_co_u32_e32 v198, vcc, s5, v198
	s_nop 0
	v_addc_co_u32_e32 v199, vcc, 0, v199, vcc
	global_load_dword v179, v[198:199], off
	v_add_co_u32_e32 v198, vcc, s5, v198
	s_nop 0
	v_addc_co_u32_e32 v199, vcc, 0, v199, vcc
	global_load_dword v180, v[198:199], off
	v_add_co_u32_e32 v198, vcc, s5, v198
	s_nop 0
	v_addc_co_u32_e32 v199, vcc, 0, v199, vcc
	global_load_dword v181, v[198:199], off
	v_add_co_u32_e32 v198, vcc, s5, v198
	s_nop 0
	v_addc_co_u32_e32 v199, vcc, 0, v199, vcc
	global_load_dword v182, v[198:199], off
	v_add_co_u32_e32 v198, vcc, s5, v198
	s_nop 0
	v_addc_co_u32_e32 v199, vcc, 0, v199, vcc
	global_load_dword v183, v[198:199], off
	v_add_co_u32_e32 v198, vcc, s5, v198
	s_nop 0
	v_addc_co_u32_e32 v199, vcc, 0, v199, vcc
	global_load_dword v184, v[198:199], off
	v_add_co_u32_e32 v198, vcc, s5, v198
	s_nop 0
	v_addc_co_u32_e32 v199, vcc, 0, v199, vcc
	global_load_dword v185, v[198:199], off
	v_add_co_u32_e32 v198, vcc, s5, v198
	s_nop 0
	v_addc_co_u32_e32 v199, vcc, 0, v199, vcc
	global_load_dword v186, v[198:199], off
	v_add_co_u32_e32 v198, vcc, s5, v198
	s_nop 0
	v_addc_co_u32_e32 v199, vcc, 0, v199, vcc
	global_load_dword v187, v[198:199], off
	v_add_co_u32_e32 v198, vcc, s5, v198
	s_nop 0
	v_addc_co_u32_e32 v199, vcc, 0, v199, vcc
	global_load_dword v188, v[198:199], off
	v_add_co_u32_e32 v198, vcc, s5, v198
	s_nop 0
	v_addc_co_u32_e32 v199, vcc, 0, v199, vcc
	global_load_dword v189, v[198:199], off
	v_add_co_u32_e32 v198, vcc, s5, v198
	s_nop 0
	v_addc_co_u32_e32 v199, vcc, 0, v199, vcc
.LBB0_385:
	ds_read_b128 v[10:13], v111
	ds_read_b128 v[6:9], v111 offset:16
	ds_read_b128 v[2:5], v111 offset:512
	ds_read_b128 v[14:17], v111 offset:528
	ds_read_b128 v[38:41], v111 offset:1024
	ds_read_b128 v[34:37], v111 offset:1040
	ds_read_b128 v[26:29], v111 offset:1536
	ds_read_b128 v[18:21], v111 offset:1552
	ds_read_b128 v[54:57], v111 offset:2048
	ds_read_b128 v[46:49], v111 offset:2064
	ds_read_b128 v[30:33], v111 offset:2560
	ds_read_b128 v[22:25], v111 offset:2576
	ds_read_b128 v[66:69], v111 offset:3072
	ds_read_b128 v[70:73], v111 offset:3088
	ds_read_b128 v[58:61], v111 offset:3584
	ds_read_b128 v[42:45], v111 offset:3600
	ds_read_b128 v[62:65], v111 offset:4096
	ds_read_b128 v[50:53], v111 offset:4112
	s_waitcnt lgkmcnt(14)
	v_mov_b32_e32 v126, v10
	v_mov_b32_e32 v127, v2
	s_waitcnt lgkmcnt(13)
	v_mov_b32_e32 v128, v38
	s_waitcnt lgkmcnt(11)
	v_mov_b32_e32 v129, v26
	s_waitcnt lgkmcnt(9)
	v_mov_b32_e32 v130, v54
	s_waitcnt lgkmcnt(7)
	v_mov_b32_e32 v131, v30
	s_waitcnt lgkmcnt(5)
	v_mov_b32_e32 v132, v66
	s_waitcnt lgkmcnt(3)
	v_mov_b32_e32 v133, v58
	v_mov_b32_e32 v2, v11
	v_mov_b32_e32 v26, v39
	v_mov_b32_e32 v30, v55
	v_mov_b32_e32 v58, v67
	v_mov_b32_e32 v10, v12
	v_mov_b32_e32 v11, v4
	v_mov_b32_e32 v38, v40
	v_mov_b32_e32 v39, v28
	v_mov_b32_e32 v54, v56
	v_mov_b32_e32 v55, v32
	v_mov_b32_e32 v66, v68
	v_mov_b32_e32 v67, v60
	v_mov_b32_e32 v4, v13
	v_mov_b32_e32 v28, v41
	v_mov_b32_e32 v32, v57
	v_mov_b32_e32 v60, v69
	v_mov_b32_e32 v12, v6
	v_mov_b32_e32 v13, v14
	v_mov_b32_e32 v40, v34
	v_mov_b32_e32 v41, v18
	v_mov_b32_e32 v56, v46
	v_mov_b32_e32 v57, v22
	v_mov_b32_e32 v68, v70
	s_waitcnt lgkmcnt(2)
	v_mov_b32_e32 v69, v42
	v_mov_b32_e32 v14, v7
	v_mov_b32_e32 v18, v35
	v_mov_b32_e32 v22, v47
	v_mov_b32_e32 v42, v71
	v_mov_b32_e32 v6, v8
	v_mov_b32_e32 v7, v16
	v_mov_b32_e32 v34, v36
	v_mov_b32_e32 v35, v20
	v_mov_b32_e32 v46, v48
	v_mov_b32_e32 v47, v24
	v_mov_b32_e32 v70, v72
	v_mov_b32_e32 v71, v44
	v_mov_b32_e32 v16, v9
	v_mov_b32_e32 v20, v37
	v_mov_b32_e32 v24, v49
	v_mov_b32_e32 v44, v73
	v_add_u32_e32 v111, 32, v111
	s_waitcnt vmcnt(55)
	v_pk_fma_f32 v[8:9], v[134:135], v[126:127], v[94:95] op_sel_hi:[0,1,1]
	v_pk_fma_f32 v[36:37], v[134:135], v[128:129], v[92:93] op_sel_hi:[0,1,1]
	v_pk_fma_f32 v[48:49], v[134:135], v[130:131], v[90:91] op_sel_hi:[0,1,1]
	v_pk_fma_f32 v[72:73], v[134:135], v[132:133], v[88:89] op_sel_hi:[0,1,1]
	s_waitcnt lgkmcnt(1)
	v_fmac_f32_e32 v0, v134, v62
	s_waitcnt vmcnt(54)
	v_pk_fma_f32 v[2:3], v[134:135], v[2:3], v[8:9] op_sel:[1,0,0] op_sel_hi:[1,1,1]
	v_pk_fma_f32 v[8:9], v[134:135], v[26:27], v[36:37] op_sel:[1,0,0] op_sel_hi:[1,1,1]
	v_pk_fma_f32 v[26:27], v[134:135], v[30:31], v[48:49] op_sel:[1,0,0] op_sel_hi:[1,1,1]
	v_pk_fma_f32 v[30:31], v[134:135], v[58:59], v[72:73] op_sel:[1,0,0] op_sel_hi:[1,1,1]
	v_fmac_f32_e32 v0, v135, v63
	s_waitcnt vmcnt(53)
	v_pk_fma_f32 v[2:3], v[136:137], v[10:11], v[2:3] op_sel_hi:[0,1,1]
	v_pk_fma_f32 v[8:9], v[136:137], v[38:39], v[8:9] op_sel_hi:[0,1,1]
	v_pk_fma_f32 v[10:11], v[136:137], v[54:55], v[26:27] op_sel_hi:[0,1,1]
	v_pk_fma_f32 v[26:27], v[136:137], v[66:67], v[30:31] op_sel_hi:[0,1,1]
	v_fmac_f32_e32 v0, v136, v64
	s_waitcnt vmcnt(52)
	v_pk_fma_f32 v[2:3], v[136:137], v[4:5], v[2:3] op_sel:[1,0,0] op_sel_hi:[1,1,1]
	v_pk_fma_f32 v[4:5], v[136:137], v[28:29], v[8:9] op_sel:[1,0,0] op_sel_hi:[1,1,1]
	v_pk_fma_f32 v[8:9], v[136:137], v[32:33], v[10:11] op_sel:[1,0,0] op_sel_hi:[1,1,1]
	v_pk_fma_f32 v[10:11], v[136:137], v[60:61], v[26:27] op_sel:[1,0,0] op_sel_hi:[1,1,1]
	v_fmac_f32_e32 v0, v137, v65
	s_waitcnt vmcnt(51)
	v_pk_fma_f32 v[2:3], v[138:139], v[12:13], v[2:3] op_sel_hi:[0,1,1]
	v_pk_fma_f32 v[4:5], v[138:139], v[40:41], v[4:5] op_sel_hi:[0,1,1]
	v_pk_fma_f32 v[8:9], v[138:139], v[56:57], v[8:9] op_sel_hi:[0,1,1]
	v_pk_fma_f32 v[10:11], v[138:139], v[68:69], v[10:11] op_sel_hi:[0,1,1]
	s_waitcnt lgkmcnt(0)
	v_fmac_f32_e32 v0, v138, v50
	s_waitcnt vmcnt(50)
	v_pk_fma_f32 v[2:3], v[138:139], v[14:15], v[2:3] op_sel:[1,0,0] op_sel_hi:[1,1,1]
	v_pk_fma_f32 v[4:5], v[138:139], v[18:19], v[4:5] op_sel:[1,0,0] op_sel_hi:[1,1,1]
	v_pk_fma_f32 v[8:9], v[138:139], v[22:23], v[8:9] op_sel:[1,0,0] op_sel_hi:[1,1,1]
	v_pk_fma_f32 v[10:11], v[138:139], v[42:43], v[10:11] op_sel:[1,0,0] op_sel_hi:[1,1,1]
	v_fmac_f32_e32 v0, v139, v51
	s_waitcnt vmcnt(49)
	v_pk_fma_f32 v[2:3], v[140:141], v[6:7], v[2:3] op_sel_hi:[0,1,1]
	v_pk_fma_f32 v[4:5], v[140:141], v[34:35], v[4:5] op_sel_hi:[0,1,1]
	v_pk_fma_f32 v[6:7], v[140:141], v[46:47], v[8:9] op_sel_hi:[0,1,1]
	v_pk_fma_f32 v[8:9], v[140:141], v[70:71], v[10:11] op_sel_hi:[0,1,1]
	v_fmac_f32_e32 v0, v140, v52
	s_waitcnt vmcnt(48)
	v_pk_fma_f32 v[94:95], v[140:141], v[16:17], v[2:3] op_sel:[1,0,0] op_sel_hi:[1,1,1]
	v_pk_fma_f32 v[92:93], v[140:141], v[20:21], v[4:5] op_sel:[1,0,0] op_sel_hi:[1,1,1]
	v_pk_fma_f32 v[90:91], v[140:141], v[24:25], v[6:7] op_sel:[1,0,0] op_sel_hi:[1,1,1]
	v_pk_fma_f32 v[88:89], v[140:141], v[44:45], v[8:9] op_sel:[1,0,0] op_sel_hi:[1,1,1]
	v_fmac_f32_e32 v0, v141, v53
	global_load_dword v190, v[198:199], off
	v_add_co_u32_e32 v198, vcc, s5, v198
	s_nop 0
	v_addc_co_u32_e32 v199, vcc, 0, v199, vcc
	global_load_dword v191, v[198:199], off
	v_add_co_u32_e32 v198, vcc, s5, v198
	s_nop 0
	v_addc_co_u32_e32 v199, vcc, 0, v199, vcc
	global_load_dword v192, v[198:199], off
	v_add_co_u32_e32 v198, vcc, s5, v198
	s_nop 0
	v_addc_co_u32_e32 v199, vcc, 0, v199, vcc
	global_load_dword v193, v[198:199], off
	v_add_co_u32_e32 v198, vcc, s5, v198
	s_nop 0
	v_addc_co_u32_e32 v199, vcc, 0, v199, vcc
	global_load_dword v194, v[198:199], off
	v_add_co_u32_e32 v198, vcc, s5, v198
	s_nop 0
	v_addc_co_u32_e32 v199, vcc, 0, v199, vcc
	global_load_dword v195, v[198:199], off
	v_add_co_u32_e32 v198, vcc, s5, v198
	s_nop 0
	v_addc_co_u32_e32 v199, vcc, 0, v199, vcc
	global_load_dword v196, v[198:199], off
	v_add_co_u32_e32 v198, vcc, s5, v198
	s_nop 0
	v_addc_co_u32_e32 v199, vcc, 0, v199, vcc
	global_load_dword v197, v[198:199], off
	v_add_co_u32_e32 v198, vcc, s5, v198
	s_nop 0
	v_addc_co_u32_e32 v199, vcc, 0, v199, vcc
	ds_read_b128 v[10:13], v111
	ds_read_b128 v[6:9], v111 offset:16
	ds_read_b128 v[2:5], v111 offset:512
	ds_read_b128 v[14:17], v111 offset:528
	ds_read_b128 v[38:41], v111 offset:1024
	ds_read_b128 v[34:37], v111 offset:1040
	ds_read_b128 v[26:29], v111 offset:1536
	ds_read_b128 v[18:21], v111 offset:1552
	ds_read_b128 v[54:57], v111 offset:2048
	ds_read_b128 v[46:49], v111 offset:2064
	ds_read_b128 v[30:33], v111 offset:2560
	ds_read_b128 v[22:25], v111 offset:2576
	ds_read_b128 v[66:69], v111 offset:3072
	ds_read_b128 v[70:73], v111 offset:3088
	ds_read_b128 v[58:61], v111 offset:3584
	ds_read_b128 v[42:45], v111 offset:3600
	ds_read_b128 v[62:65], v111 offset:4096
	ds_read_b128 v[50:53], v111 offset:4112
	s_waitcnt lgkmcnt(14)
	v_mov_b32_e32 v126, v10
	v_mov_b32_e32 v127, v2
	s_waitcnt lgkmcnt(13)
	v_mov_b32_e32 v128, v38
	s_waitcnt lgkmcnt(11)
	v_mov_b32_e32 v129, v26
	s_waitcnt lgkmcnt(9)
	v_mov_b32_e32 v130, v54
	s_waitcnt lgkmcnt(7)
	v_mov_b32_e32 v131, v30
	s_waitcnt lgkmcnt(5)
	v_mov_b32_e32 v132, v66
	s_waitcnt lgkmcnt(3)
	v_mov_b32_e32 v133, v58
	v_mov_b32_e32 v2, v11
	v_mov_b32_e32 v26, v39
	v_mov_b32_e32 v30, v55
	v_mov_b32_e32 v58, v67
	v_mov_b32_e32 v10, v12
	v_mov_b32_e32 v11, v4
	v_mov_b32_e32 v38, v40
	v_mov_b32_e32 v39, v28
	v_mov_b32_e32 v54, v56
	v_mov_b32_e32 v55, v32
	v_mov_b32_e32 v66, v68
	v_mov_b32_e32 v67, v60
	v_mov_b32_e32 v4, v13
	v_mov_b32_e32 v28, v41
	v_mov_b32_e32 v32, v57
	v_mov_b32_e32 v60, v69
	v_mov_b32_e32 v12, v6
	v_mov_b32_e32 v13, v14
	v_mov_b32_e32 v40, v34
	v_mov_b32_e32 v41, v18
	v_mov_b32_e32 v56, v46
	v_mov_b32_e32 v57, v22
	v_mov_b32_e32 v68, v70
	s_waitcnt lgkmcnt(2)
	v_mov_b32_e32 v69, v42
	v_mov_b32_e32 v14, v7
	v_mov_b32_e32 v18, v35
	v_mov_b32_e32 v22, v47
	v_mov_b32_e32 v42, v71
	v_mov_b32_e32 v6, v8
	v_mov_b32_e32 v7, v16
	v_mov_b32_e32 v34, v36
	v_mov_b32_e32 v35, v20
	v_mov_b32_e32 v46, v48
	v_mov_b32_e32 v47, v24
	v_mov_b32_e32 v70, v72
	v_mov_b32_e32 v71, v44
	v_mov_b32_e32 v16, v9
	v_mov_b32_e32 v20, v37
	v_mov_b32_e32 v24, v49
	v_mov_b32_e32 v44, v73
	v_add_u32_e32 v111, 32, v111
	s_waitcnt vmcnt(55)
	v_pk_fma_f32 v[8:9], v[142:143], v[126:127], v[94:95] op_sel_hi:[0,1,1]
	v_pk_fma_f32 v[36:37], v[142:143], v[128:129], v[92:93] op_sel_hi:[0,1,1]
	v_pk_fma_f32 v[48:49], v[142:143], v[130:131], v[90:91] op_sel_hi:[0,1,1]
	v_pk_fma_f32 v[72:73], v[142:143], v[132:133], v[88:89] op_sel_hi:[0,1,1]
	s_waitcnt lgkmcnt(1)
	v_fmac_f32_e32 v0, v142, v62
	s_waitcnt vmcnt(54)
	v_pk_fma_f32 v[2:3], v[142:143], v[2:3], v[8:9] op_sel:[1,0,0] op_sel_hi:[1,1,1]
	v_pk_fma_f32 v[8:9], v[142:143], v[26:27], v[36:37] op_sel:[1,0,0] op_sel_hi:[1,1,1]
	v_pk_fma_f32 v[26:27], v[142:143], v[30:31], v[48:49] op_sel:[1,0,0] op_sel_hi:[1,1,1]
	v_pk_fma_f32 v[30:31], v[142:143], v[58:59], v[72:73] op_sel:[1,0,0] op_sel_hi:[1,1,1]
	v_fmac_f32_e32 v0, v143, v63
	s_waitcnt vmcnt(53)
	v_pk_fma_f32 v[2:3], v[144:145], v[10:11], v[2:3] op_sel_hi:[0,1,1]
	v_pk_fma_f32 v[8:9], v[144:145], v[38:39], v[8:9] op_sel_hi:[0,1,1]
	v_pk_fma_f32 v[10:11], v[144:145], v[54:55], v[26:27] op_sel_hi:[0,1,1]
	v_pk_fma_f32 v[26:27], v[144:145], v[66:67], v[30:31] op_sel_hi:[0,1,1]
	v_fmac_f32_e32 v0, v144, v64
	s_waitcnt vmcnt(52)
	v_pk_fma_f32 v[2:3], v[144:145], v[4:5], v[2:3] op_sel:[1,0,0] op_sel_hi:[1,1,1]
	v_pk_fma_f32 v[4:5], v[144:145], v[28:29], v[8:9] op_sel:[1,0,0] op_sel_hi:[1,1,1]
	v_pk_fma_f32 v[8:9], v[144:145], v[32:33], v[10:11] op_sel:[1,0,0] op_sel_hi:[1,1,1]
	v_pk_fma_f32 v[10:11], v[144:145], v[60:61], v[26:27] op_sel:[1,0,0] op_sel_hi:[1,1,1]
	v_fmac_f32_e32 v0, v145, v65
	s_waitcnt vmcnt(51)
	v_pk_fma_f32 v[2:3], v[146:147], v[12:13], v[2:3] op_sel_hi:[0,1,1]
	v_pk_fma_f32 v[4:5], v[146:147], v[40:41], v[4:5] op_sel_hi:[0,1,1]
	v_pk_fma_f32 v[8:9], v[146:147], v[56:57], v[8:9] op_sel_hi:[0,1,1]
	v_pk_fma_f32 v[10:11], v[146:147], v[68:69], v[10:11] op_sel_hi:[0,1,1]
	s_waitcnt lgkmcnt(0)
	v_fmac_f32_e32 v0, v146, v50
	s_waitcnt vmcnt(50)
	v_pk_fma_f32 v[2:3], v[146:147], v[14:15], v[2:3] op_sel:[1,0,0] op_sel_hi:[1,1,1]
	v_pk_fma_f32 v[4:5], v[146:147], v[18:19], v[4:5] op_sel:[1,0,0] op_sel_hi:[1,1,1]
	v_pk_fma_f32 v[8:9], v[146:147], v[22:23], v[8:9] op_sel:[1,0,0] op_sel_hi:[1,1,1]
	v_pk_fma_f32 v[10:11], v[146:147], v[42:43], v[10:11] op_sel:[1,0,0] op_sel_hi:[1,1,1]
	v_fmac_f32_e32 v0, v147, v51
	s_waitcnt vmcnt(49)
	v_pk_fma_f32 v[2:3], v[148:149], v[6:7], v[2:3] op_sel_hi:[0,1,1]
	v_pk_fma_f32 v[4:5], v[148:149], v[34:35], v[4:5] op_sel_hi:[0,1,1]
	v_pk_fma_f32 v[6:7], v[148:149], v[46:47], v[8:9] op_sel_hi:[0,1,1]
	v_pk_fma_f32 v[8:9], v[148:149], v[70:71], v[10:11] op_sel_hi:[0,1,1]
	v_fmac_f32_e32 v0, v148, v52
	s_waitcnt vmcnt(48)
	v_pk_fma_f32 v[94:95], v[148:149], v[16:17], v[2:3] op_sel:[1,0,0] op_sel_hi:[1,1,1]
	v_pk_fma_f32 v[92:93], v[148:149], v[20:21], v[4:5] op_sel:[1,0,0] op_sel_hi:[1,1,1]
	v_pk_fma_f32 v[90:91], v[148:149], v[24:25], v[6:7] op_sel:[1,0,0] op_sel_hi:[1,1,1]
	v_pk_fma_f32 v[88:89], v[148:149], v[44:45], v[8:9] op_sel:[1,0,0] op_sel_hi:[1,1,1]
	v_fmac_f32_e32 v0, v149, v53
	ds_read_b128 v[10:13], v111
	ds_read_b128 v[6:9], v111 offset:16
	ds_read_b128 v[2:5], v111 offset:512
	ds_read_b128 v[14:17], v111 offset:528
	ds_read_b128 v[38:41], v111 offset:1024
	ds_read_b128 v[34:37], v111 offset:1040
	ds_read_b128 v[26:29], v111 offset:1536
	ds_read_b128 v[18:21], v111 offset:1552
	ds_read_b128 v[54:57], v111 offset:2048
	ds_read_b128 v[46:49], v111 offset:2064
	ds_read_b128 v[30:33], v111 offset:2560
	ds_read_b128 v[22:25], v111 offset:2576
	ds_read_b128 v[66:69], v111 offset:3072
	ds_read_b128 v[70:73], v111 offset:3088
	ds_read_b128 v[58:61], v111 offset:3584
	ds_read_b128 v[42:45], v111 offset:3600
	ds_read_b128 v[62:65], v111 offset:4096
	ds_read_b128 v[50:53], v111 offset:4112
	s_waitcnt lgkmcnt(14)
	v_mov_b32_e32 v126, v10
	v_mov_b32_e32 v127, v2
	s_waitcnt lgkmcnt(13)
	v_mov_b32_e32 v128, v38
	s_waitcnt lgkmcnt(11)
	v_mov_b32_e32 v129, v26
	s_waitcnt lgkmcnt(9)
	v_mov_b32_e32 v130, v54
	s_waitcnt lgkmcnt(7)
	v_mov_b32_e32 v131, v30
	s_waitcnt lgkmcnt(5)
	v_mov_b32_e32 v132, v66
	s_waitcnt lgkmcnt(3)
	v_mov_b32_e32 v133, v58
	v_mov_b32_e32 v2, v11
	v_mov_b32_e32 v26, v39
	v_mov_b32_e32 v30, v55
	v_mov_b32_e32 v58, v67
	v_mov_b32_e32 v10, v12
	v_mov_b32_e32 v11, v4
	v_mov_b32_e32 v38, v40
	v_mov_b32_e32 v39, v28
	v_mov_b32_e32 v54, v56
	v_mov_b32_e32 v55, v32
	v_mov_b32_e32 v66, v68
	v_mov_b32_e32 v67, v60
	v_mov_b32_e32 v4, v13
	v_mov_b32_e32 v28, v41
	v_mov_b32_e32 v32, v57
	v_mov_b32_e32 v60, v69
	v_mov_b32_e32 v12, v6
	v_mov_b32_e32 v13, v14
	v_mov_b32_e32 v40, v34
	v_mov_b32_e32 v41, v18
	v_mov_b32_e32 v56, v46
	v_mov_b32_e32 v57, v22
	v_mov_b32_e32 v68, v70
	s_waitcnt lgkmcnt(2)
	v_mov_b32_e32 v69, v42
	v_mov_b32_e32 v14, v7
	v_mov_b32_e32 v18, v35
	v_mov_b32_e32 v22, v47
	v_mov_b32_e32 v42, v71
	v_mov_b32_e32 v6, v8
	v_mov_b32_e32 v7, v16
	v_mov_b32_e32 v34, v36
	v_mov_b32_e32 v35, v20
	v_mov_b32_e32 v46, v48
	v_mov_b32_e32 v47, v24
	v_mov_b32_e32 v70, v72
	v_mov_b32_e32 v71, v44
	v_mov_b32_e32 v16, v9
	v_mov_b32_e32 v20, v37
	v_mov_b32_e32 v24, v49
	v_mov_b32_e32 v44, v73
	v_add_u32_e32 v111, 32, v111
	s_waitcnt vmcnt(47)
	v_pk_fma_f32 v[8:9], v[150:151], v[126:127], v[94:95] op_sel_hi:[0,1,1]
	v_pk_fma_f32 v[36:37], v[150:151], v[128:129], v[92:93] op_sel_hi:[0,1,1]
	v_pk_fma_f32 v[48:49], v[150:151], v[130:131], v[90:91] op_sel_hi:[0,1,1]
	v_pk_fma_f32 v[72:73], v[150:151], v[132:133], v[88:89] op_sel_hi:[0,1,1]
	s_waitcnt lgkmcnt(1)
	v_fmac_f32_e32 v0, v150, v62
	s_waitcnt vmcnt(46)
	v_pk_fma_f32 v[2:3], v[150:151], v[2:3], v[8:9] op_sel:[1,0,0] op_sel_hi:[1,1,1]
	v_pk_fma_f32 v[8:9], v[150:151], v[26:27], v[36:37] op_sel:[1,0,0] op_sel_hi:[1,1,1]
	v_pk_fma_f32 v[26:27], v[150:151], v[30:31], v[48:49] op_sel:[1,0,0] op_sel_hi:[1,1,1]
	v_pk_fma_f32 v[30:31], v[150:151], v[58:59], v[72:73] op_sel:[1,0,0] op_sel_hi:[1,1,1]
	v_fmac_f32_e32 v0, v151, v63
	s_waitcnt vmcnt(45)
	v_pk_fma_f32 v[2:3], v[152:153], v[10:11], v[2:3] op_sel_hi:[0,1,1]
	v_pk_fma_f32 v[8:9], v[152:153], v[38:39], v[8:9] op_sel_hi:[0,1,1]
	v_pk_fma_f32 v[10:11], v[152:153], v[54:55], v[26:27] op_sel_hi:[0,1,1]
	v_pk_fma_f32 v[26:27], v[152:153], v[66:67], v[30:31] op_sel_hi:[0,1,1]
	v_fmac_f32_e32 v0, v152, v64
	s_waitcnt vmcnt(44)
	v_pk_fma_f32 v[2:3], v[152:153], v[4:5], v[2:3] op_sel:[1,0,0] op_sel_hi:[1,1,1]
	v_pk_fma_f32 v[4:5], v[152:153], v[28:29], v[8:9] op_sel:[1,0,0] op_sel_hi:[1,1,1]
	v_pk_fma_f32 v[8:9], v[152:153], v[32:33], v[10:11] op_sel:[1,0,0] op_sel_hi:[1,1,1]
	v_pk_fma_f32 v[10:11], v[152:153], v[60:61], v[26:27] op_sel:[1,0,0] op_sel_hi:[1,1,1]
	v_fmac_f32_e32 v0, v153, v65
	s_waitcnt vmcnt(43)
	v_pk_fma_f32 v[2:3], v[154:155], v[12:13], v[2:3] op_sel_hi:[0,1,1]
	v_pk_fma_f32 v[4:5], v[154:155], v[40:41], v[4:5] op_sel_hi:[0,1,1]
	v_pk_fma_f32 v[8:9], v[154:155], v[56:57], v[8:9] op_sel_hi:[0,1,1]
	v_pk_fma_f32 v[10:11], v[154:155], v[68:69], v[10:11] op_sel_hi:[0,1,1]
	s_waitcnt lgkmcnt(0)
	v_fmac_f32_e32 v0, v154, v50
	s_waitcnt vmcnt(42)
	v_pk_fma_f32 v[2:3], v[154:155], v[14:15], v[2:3] op_sel:[1,0,0] op_sel_hi:[1,1,1]
	v_pk_fma_f32 v[4:5], v[154:155], v[18:19], v[4:5] op_sel:[1,0,0] op_sel_hi:[1,1,1]
	v_pk_fma_f32 v[8:9], v[154:155], v[22:23], v[8:9] op_sel:[1,0,0] op_sel_hi:[1,1,1]
	v_pk_fma_f32 v[10:11], v[154:155], v[42:43], v[10:11] op_sel:[1,0,0] op_sel_hi:[1,1,1]
	v_fmac_f32_e32 v0, v155, v51
	s_waitcnt vmcnt(41)
	v_pk_fma_f32 v[2:3], v[156:157], v[6:7], v[2:3] op_sel_hi:[0,1,1]
	v_pk_fma_f32 v[4:5], v[156:157], v[34:35], v[4:5] op_sel_hi:[0,1,1]
	v_pk_fma_f32 v[6:7], v[156:157], v[46:47], v[8:9] op_sel_hi:[0,1,1]
	v_pk_fma_f32 v[8:9], v[156:157], v[70:71], v[10:11] op_sel_hi:[0,1,1]
	v_fmac_f32_e32 v0, v156, v52
	s_waitcnt vmcnt(40)
	v_pk_fma_f32 v[94:95], v[156:157], v[16:17], v[2:3] op_sel:[1,0,0] op_sel_hi:[1,1,1]
	v_pk_fma_f32 v[92:93], v[156:157], v[20:21], v[4:5] op_sel:[1,0,0] op_sel_hi:[1,1,1]
	v_pk_fma_f32 v[90:91], v[156:157], v[24:25], v[6:7] op_sel:[1,0,0] op_sel_hi:[1,1,1]
	v_pk_fma_f32 v[88:89], v[156:157], v[44:45], v[8:9] op_sel:[1,0,0] op_sel_hi:[1,1,1]
	v_fmac_f32_e32 v0, v157, v53
	ds_read_b128 v[10:13], v111
	ds_read_b128 v[6:9], v111 offset:16
	ds_read_b128 v[2:5], v111 offset:512
	ds_read_b128 v[14:17], v111 offset:528
	ds_read_b128 v[38:41], v111 offset:1024
	ds_read_b128 v[34:37], v111 offset:1040
	ds_read_b128 v[26:29], v111 offset:1536
	ds_read_b128 v[18:21], v111 offset:1552
	ds_read_b128 v[54:57], v111 offset:2048
	ds_read_b128 v[46:49], v111 offset:2064
	ds_read_b128 v[30:33], v111 offset:2560
	ds_read_b128 v[22:25], v111 offset:2576
	ds_read_b128 v[66:69], v111 offset:3072
	ds_read_b128 v[70:73], v111 offset:3088
	ds_read_b128 v[58:61], v111 offset:3584
	ds_read_b128 v[42:45], v111 offset:3600
	ds_read_b128 v[62:65], v111 offset:4096
	ds_read_b128 v[50:53], v111 offset:4112
	s_waitcnt lgkmcnt(14)
	v_mov_b32_e32 v126, v10
	v_mov_b32_e32 v127, v2
	s_waitcnt lgkmcnt(13)
	v_mov_b32_e32 v128, v38
	s_waitcnt lgkmcnt(11)
	v_mov_b32_e32 v129, v26
	s_waitcnt lgkmcnt(9)
	v_mov_b32_e32 v130, v54
	s_waitcnt lgkmcnt(7)
	v_mov_b32_e32 v131, v30
	s_waitcnt lgkmcnt(5)
	v_mov_b32_e32 v132, v66
	s_waitcnt lgkmcnt(3)
	v_mov_b32_e32 v133, v58
	v_mov_b32_e32 v2, v11
	v_mov_b32_e32 v26, v39
	v_mov_b32_e32 v30, v55
	v_mov_b32_e32 v58, v67
	v_mov_b32_e32 v10, v12
	v_mov_b32_e32 v11, v4
	v_mov_b32_e32 v38, v40
	v_mov_b32_e32 v39, v28
	v_mov_b32_e32 v54, v56
	v_mov_b32_e32 v55, v32
	v_mov_b32_e32 v66, v68
	v_mov_b32_e32 v67, v60
	v_mov_b32_e32 v4, v13
	v_mov_b32_e32 v28, v41
	v_mov_b32_e32 v32, v57
	v_mov_b32_e32 v60, v69
	v_mov_b32_e32 v12, v6
	v_mov_b32_e32 v13, v14
	v_mov_b32_e32 v40, v34
	v_mov_b32_e32 v41, v18
	v_mov_b32_e32 v56, v46
	v_mov_b32_e32 v57, v22
	v_mov_b32_e32 v68, v70
	s_waitcnt lgkmcnt(2)
	v_mov_b32_e32 v69, v42
	v_mov_b32_e32 v14, v7
	v_mov_b32_e32 v18, v35
	v_mov_b32_e32 v22, v47
	v_mov_b32_e32 v42, v71
	v_mov_b32_e32 v6, v8
	v_mov_b32_e32 v7, v16
	v_mov_b32_e32 v34, v36
	v_mov_b32_e32 v35, v20
	v_mov_b32_e32 v46, v48
	v_mov_b32_e32 v47, v24
	v_mov_b32_e32 v70, v72
	v_mov_b32_e32 v71, v44
	v_mov_b32_e32 v16, v9
	v_mov_b32_e32 v20, v37
	v_mov_b32_e32 v24, v49
	v_mov_b32_e32 v44, v73
	v_add_u32_e32 v111, 32, v111
	s_waitcnt vmcnt(39)
	v_pk_fma_f32 v[8:9], v[158:159], v[126:127], v[94:95] op_sel_hi:[0,1,1]
	v_pk_fma_f32 v[36:37], v[158:159], v[128:129], v[92:93] op_sel_hi:[0,1,1]
	v_pk_fma_f32 v[48:49], v[158:159], v[130:131], v[90:91] op_sel_hi:[0,1,1]
	v_pk_fma_f32 v[72:73], v[158:159], v[132:133], v[88:89] op_sel_hi:[0,1,1]
	s_waitcnt lgkmcnt(1)
	v_fmac_f32_e32 v0, v158, v62
	s_waitcnt vmcnt(38)
	v_pk_fma_f32 v[2:3], v[158:159], v[2:3], v[8:9] op_sel:[1,0,0] op_sel_hi:[1,1,1]
	v_pk_fma_f32 v[8:9], v[158:159], v[26:27], v[36:37] op_sel:[1,0,0] op_sel_hi:[1,1,1]
	v_pk_fma_f32 v[26:27], v[158:159], v[30:31], v[48:49] op_sel:[1,0,0] op_sel_hi:[1,1,1]
	v_pk_fma_f32 v[30:31], v[158:159], v[58:59], v[72:73] op_sel:[1,0,0] op_sel_hi:[1,1,1]
	v_fmac_f32_e32 v0, v159, v63
	s_waitcnt vmcnt(37)
	v_pk_fma_f32 v[2:3], v[160:161], v[10:11], v[2:3] op_sel_hi:[0,1,1]
	v_pk_fma_f32 v[8:9], v[160:161], v[38:39], v[8:9] op_sel_hi:[0,1,1]
	v_pk_fma_f32 v[10:11], v[160:161], v[54:55], v[26:27] op_sel_hi:[0,1,1]
	v_pk_fma_f32 v[26:27], v[160:161], v[66:67], v[30:31] op_sel_hi:[0,1,1]
	v_fmac_f32_e32 v0, v160, v64
	s_waitcnt vmcnt(36)
	v_pk_fma_f32 v[2:3], v[160:161], v[4:5], v[2:3] op_sel:[1,0,0] op_sel_hi:[1,1,1]
	v_pk_fma_f32 v[4:5], v[160:161], v[28:29], v[8:9] op_sel:[1,0,0] op_sel_hi:[1,1,1]
	v_pk_fma_f32 v[8:9], v[160:161], v[32:33], v[10:11] op_sel:[1,0,0] op_sel_hi:[1,1,1]
	v_pk_fma_f32 v[10:11], v[160:161], v[60:61], v[26:27] op_sel:[1,0,0] op_sel_hi:[1,1,1]
	v_fmac_f32_e32 v0, v161, v65
	s_waitcnt vmcnt(35)
	v_pk_fma_f32 v[2:3], v[162:163], v[12:13], v[2:3] op_sel_hi:[0,1,1]
	v_pk_fma_f32 v[4:5], v[162:163], v[40:41], v[4:5] op_sel_hi:[0,1,1]
	v_pk_fma_f32 v[8:9], v[162:163], v[56:57], v[8:9] op_sel_hi:[0,1,1]
	v_pk_fma_f32 v[10:11], v[162:163], v[68:69], v[10:11] op_sel_hi:[0,1,1]
	s_waitcnt lgkmcnt(0)
	v_fmac_f32_e32 v0, v162, v50
	s_waitcnt vmcnt(34)
	v_pk_fma_f32 v[2:3], v[162:163], v[14:15], v[2:3] op_sel:[1,0,0] op_sel_hi:[1,1,1]
	v_pk_fma_f32 v[4:5], v[162:163], v[18:19], v[4:5] op_sel:[1,0,0] op_sel_hi:[1,1,1]
	v_pk_fma_f32 v[8:9], v[162:163], v[22:23], v[8:9] op_sel:[1,0,0] op_sel_hi:[1,1,1]
	v_pk_fma_f32 v[10:11], v[162:163], v[42:43], v[10:11] op_sel:[1,0,0] op_sel_hi:[1,1,1]
	v_fmac_f32_e32 v0, v163, v51
	s_waitcnt vmcnt(33)
	v_pk_fma_f32 v[2:3], v[164:165], v[6:7], v[2:3] op_sel_hi:[0,1,1]
	v_pk_fma_f32 v[4:5], v[164:165], v[34:35], v[4:5] op_sel_hi:[0,1,1]
	v_pk_fma_f32 v[6:7], v[164:165], v[46:47], v[8:9] op_sel_hi:[0,1,1]
	v_pk_fma_f32 v[8:9], v[164:165], v[70:71], v[10:11] op_sel_hi:[0,1,1]
	v_fmac_f32_e32 v0, v164, v52
	s_waitcnt vmcnt(32)
	v_pk_fma_f32 v[94:95], v[164:165], v[16:17], v[2:3] op_sel:[1,0,0] op_sel_hi:[1,1,1]
	v_pk_fma_f32 v[92:93], v[164:165], v[20:21], v[4:5] op_sel:[1,0,0] op_sel_hi:[1,1,1]
	v_pk_fma_f32 v[90:91], v[164:165], v[24:25], v[6:7] op_sel:[1,0,0] op_sel_hi:[1,1,1]
	v_pk_fma_f32 v[88:89], v[164:165], v[44:45], v[8:9] op_sel:[1,0,0] op_sel_hi:[1,1,1]
	v_fmac_f32_e32 v0, v165, v53
	ds_read_b128 v[10:13], v111
	ds_read_b128 v[6:9], v111 offset:16
	ds_read_b128 v[2:5], v111 offset:512
	ds_read_b128 v[14:17], v111 offset:528
	ds_read_b128 v[38:41], v111 offset:1024
	ds_read_b128 v[34:37], v111 offset:1040
	ds_read_b128 v[26:29], v111 offset:1536
	ds_read_b128 v[18:21], v111 offset:1552
	ds_read_b128 v[54:57], v111 offset:2048
	ds_read_b128 v[46:49], v111 offset:2064
	ds_read_b128 v[30:33], v111 offset:2560
	ds_read_b128 v[22:25], v111 offset:2576
	ds_read_b128 v[66:69], v111 offset:3072
	ds_read_b128 v[70:73], v111 offset:3088
	ds_read_b128 v[58:61], v111 offset:3584
	ds_read_b128 v[42:45], v111 offset:3600
	ds_read_b128 v[62:65], v111 offset:4096
	ds_read_b128 v[50:53], v111 offset:4112
	s_waitcnt lgkmcnt(14)
	v_mov_b32_e32 v126, v10
	v_mov_b32_e32 v127, v2
	s_waitcnt lgkmcnt(13)
	v_mov_b32_e32 v128, v38
	s_waitcnt lgkmcnt(11)
	v_mov_b32_e32 v129, v26
	s_waitcnt lgkmcnt(9)
	v_mov_b32_e32 v130, v54
	s_waitcnt lgkmcnt(7)
	v_mov_b32_e32 v131, v30
	s_waitcnt lgkmcnt(5)
	v_mov_b32_e32 v132, v66
	s_waitcnt lgkmcnt(3)
	v_mov_b32_e32 v133, v58
	v_mov_b32_e32 v2, v11
	v_mov_b32_e32 v26, v39
	v_mov_b32_e32 v30, v55
	v_mov_b32_e32 v58, v67
	v_mov_b32_e32 v10, v12
	v_mov_b32_e32 v11, v4
	v_mov_b32_e32 v38, v40
	v_mov_b32_e32 v39, v28
	v_mov_b32_e32 v54, v56
	v_mov_b32_e32 v55, v32
	v_mov_b32_e32 v66, v68
	v_mov_b32_e32 v67, v60
	v_mov_b32_e32 v4, v13
	v_mov_b32_e32 v28, v41
	v_mov_b32_e32 v32, v57
	v_mov_b32_e32 v60, v69
	v_mov_b32_e32 v12, v6
	v_mov_b32_e32 v13, v14
	v_mov_b32_e32 v40, v34
	v_mov_b32_e32 v41, v18
	v_mov_b32_e32 v56, v46
	v_mov_b32_e32 v57, v22
	v_mov_b32_e32 v68, v70
	s_waitcnt lgkmcnt(2)
	v_mov_b32_e32 v69, v42
	v_mov_b32_e32 v14, v7
	v_mov_b32_e32 v18, v35
	v_mov_b32_e32 v22, v47
	v_mov_b32_e32 v42, v71
	v_mov_b32_e32 v6, v8
	v_mov_b32_e32 v7, v16
	v_mov_b32_e32 v34, v36
	v_mov_b32_e32 v35, v20
	v_mov_b32_e32 v46, v48
	v_mov_b32_e32 v47, v24
	v_mov_b32_e32 v70, v72
	v_mov_b32_e32 v71, v44
	v_mov_b32_e32 v16, v9
	v_mov_b32_e32 v20, v37
	v_mov_b32_e32 v24, v49
	v_mov_b32_e32 v44, v73
	v_add_u32_e32 v111, 32, v111
	s_waitcnt vmcnt(31)
	v_pk_fma_f32 v[8:9], v[166:167], v[126:127], v[94:95] op_sel_hi:[0,1,1]
	v_pk_fma_f32 v[36:37], v[166:167], v[128:129], v[92:93] op_sel_hi:[0,1,1]
	v_pk_fma_f32 v[48:49], v[166:167], v[130:131], v[90:91] op_sel_hi:[0,1,1]
	v_pk_fma_f32 v[72:73], v[166:167], v[132:133], v[88:89] op_sel_hi:[0,1,1]
	s_waitcnt lgkmcnt(1)
	v_fmac_f32_e32 v0, v166, v62
	s_waitcnt vmcnt(30)
	v_pk_fma_f32 v[2:3], v[166:167], v[2:3], v[8:9] op_sel:[1,0,0] op_sel_hi:[1,1,1]
	v_pk_fma_f32 v[8:9], v[166:167], v[26:27], v[36:37] op_sel:[1,0,0] op_sel_hi:[1,1,1]
	v_pk_fma_f32 v[26:27], v[166:167], v[30:31], v[48:49] op_sel:[1,0,0] op_sel_hi:[1,1,1]
	v_pk_fma_f32 v[30:31], v[166:167], v[58:59], v[72:73] op_sel:[1,0,0] op_sel_hi:[1,1,1]
	v_fmac_f32_e32 v0, v167, v63
	s_waitcnt vmcnt(29)
	v_pk_fma_f32 v[2:3], v[168:169], v[10:11], v[2:3] op_sel_hi:[0,1,1]
	v_pk_fma_f32 v[8:9], v[168:169], v[38:39], v[8:9] op_sel_hi:[0,1,1]
	v_pk_fma_f32 v[10:11], v[168:169], v[54:55], v[26:27] op_sel_hi:[0,1,1]
	v_pk_fma_f32 v[26:27], v[168:169], v[66:67], v[30:31] op_sel_hi:[0,1,1]
	v_fmac_f32_e32 v0, v168, v64
	s_waitcnt vmcnt(28)
	v_pk_fma_f32 v[2:3], v[168:169], v[4:5], v[2:3] op_sel:[1,0,0] op_sel_hi:[1,1,1]
	v_pk_fma_f32 v[4:5], v[168:169], v[28:29], v[8:9] op_sel:[1,0,0] op_sel_hi:[1,1,1]
	v_pk_fma_f32 v[8:9], v[168:169], v[32:33], v[10:11] op_sel:[1,0,0] op_sel_hi:[1,1,1]
	v_pk_fma_f32 v[10:11], v[168:169], v[60:61], v[26:27] op_sel:[1,0,0] op_sel_hi:[1,1,1]
	v_fmac_f32_e32 v0, v169, v65
	s_waitcnt vmcnt(27)
	v_pk_fma_f32 v[2:3], v[170:171], v[12:13], v[2:3] op_sel_hi:[0,1,1]
	v_pk_fma_f32 v[4:5], v[170:171], v[40:41], v[4:5] op_sel_hi:[0,1,1]
	v_pk_fma_f32 v[8:9], v[170:171], v[56:57], v[8:9] op_sel_hi:[0,1,1]
	v_pk_fma_f32 v[10:11], v[170:171], v[68:69], v[10:11] op_sel_hi:[0,1,1]
	s_waitcnt lgkmcnt(0)
	v_fmac_f32_e32 v0, v170, v50
	s_waitcnt vmcnt(26)
	v_pk_fma_f32 v[2:3], v[170:171], v[14:15], v[2:3] op_sel:[1,0,0] op_sel_hi:[1,1,1]
	v_pk_fma_f32 v[4:5], v[170:171], v[18:19], v[4:5] op_sel:[1,0,0] op_sel_hi:[1,1,1]
	v_pk_fma_f32 v[8:9], v[170:171], v[22:23], v[8:9] op_sel:[1,0,0] op_sel_hi:[1,1,1]
	v_pk_fma_f32 v[10:11], v[170:171], v[42:43], v[10:11] op_sel:[1,0,0] op_sel_hi:[1,1,1]
	v_fmac_f32_e32 v0, v171, v51
	s_waitcnt vmcnt(25)
	v_pk_fma_f32 v[2:3], v[172:173], v[6:7], v[2:3] op_sel_hi:[0,1,1]
	v_pk_fma_f32 v[4:5], v[172:173], v[34:35], v[4:5] op_sel_hi:[0,1,1]
	v_pk_fma_f32 v[6:7], v[172:173], v[46:47], v[8:9] op_sel_hi:[0,1,1]
	v_pk_fma_f32 v[8:9], v[172:173], v[70:71], v[10:11] op_sel_hi:[0,1,1]
	v_fmac_f32_e32 v0, v172, v52
	s_waitcnt vmcnt(24)
	v_pk_fma_f32 v[94:95], v[172:173], v[16:17], v[2:3] op_sel:[1,0,0] op_sel_hi:[1,1,1]
	v_pk_fma_f32 v[92:93], v[172:173], v[20:21], v[4:5] op_sel:[1,0,0] op_sel_hi:[1,1,1]
	v_pk_fma_f32 v[90:91], v[172:173], v[24:25], v[6:7] op_sel:[1,0,0] op_sel_hi:[1,1,1]
	v_pk_fma_f32 v[88:89], v[172:173], v[44:45], v[8:9] op_sel:[1,0,0] op_sel_hi:[1,1,1]
	v_fmac_f32_e32 v0, v173, v53
	ds_read_b128 v[10:13], v111
	ds_read_b128 v[6:9], v111 offset:16
	ds_read_b128 v[2:5], v111 offset:512
	ds_read_b128 v[14:17], v111 offset:528
	ds_read_b128 v[38:41], v111 offset:1024
	ds_read_b128 v[34:37], v111 offset:1040
	ds_read_b128 v[26:29], v111 offset:1536
	ds_read_b128 v[18:21], v111 offset:1552
	ds_read_b128 v[54:57], v111 offset:2048
	ds_read_b128 v[46:49], v111 offset:2064
	ds_read_b128 v[30:33], v111 offset:2560
	ds_read_b128 v[22:25], v111 offset:2576
	ds_read_b128 v[66:69], v111 offset:3072
	ds_read_b128 v[70:73], v111 offset:3088
	ds_read_b128 v[58:61], v111 offset:3584
	ds_read_b128 v[42:45], v111 offset:3600
	ds_read_b128 v[62:65], v111 offset:4096
	ds_read_b128 v[50:53], v111 offset:4112
	s_waitcnt lgkmcnt(14)
	v_mov_b32_e32 v126, v10
	v_mov_b32_e32 v127, v2
	s_waitcnt lgkmcnt(13)
	v_mov_b32_e32 v128, v38
	s_waitcnt lgkmcnt(11)
	v_mov_b32_e32 v129, v26
	s_waitcnt lgkmcnt(9)
	v_mov_b32_e32 v130, v54
	s_waitcnt lgkmcnt(7)
	v_mov_b32_e32 v131, v30
	s_waitcnt lgkmcnt(5)
	v_mov_b32_e32 v132, v66
	s_waitcnt lgkmcnt(3)
	v_mov_b32_e32 v133, v58
	v_mov_b32_e32 v2, v11
	v_mov_b32_e32 v26, v39
	v_mov_b32_e32 v30, v55
	v_mov_b32_e32 v58, v67
	v_mov_b32_e32 v10, v12
	v_mov_b32_e32 v11, v4
	v_mov_b32_e32 v38, v40
	v_mov_b32_e32 v39, v28
	v_mov_b32_e32 v54, v56
	v_mov_b32_e32 v55, v32
	v_mov_b32_e32 v66, v68
	v_mov_b32_e32 v67, v60
	v_mov_b32_e32 v4, v13
	v_mov_b32_e32 v28, v41
	v_mov_b32_e32 v32, v57
	v_mov_b32_e32 v60, v69
	v_mov_b32_e32 v12, v6
	v_mov_b32_e32 v13, v14
	v_mov_b32_e32 v40, v34
	v_mov_b32_e32 v41, v18
	v_mov_b32_e32 v56, v46
	v_mov_b32_e32 v57, v22
	v_mov_b32_e32 v68, v70
	s_waitcnt lgkmcnt(2)
	v_mov_b32_e32 v69, v42
	v_mov_b32_e32 v14, v7
	v_mov_b32_e32 v18, v35
	v_mov_b32_e32 v22, v47
	v_mov_b32_e32 v42, v71
	v_mov_b32_e32 v6, v8
	v_mov_b32_e32 v7, v16
	v_mov_b32_e32 v34, v36
	v_mov_b32_e32 v35, v20
	v_mov_b32_e32 v46, v48
	v_mov_b32_e32 v47, v24
	v_mov_b32_e32 v70, v72
	v_mov_b32_e32 v71, v44
	v_mov_b32_e32 v16, v9
	v_mov_b32_e32 v20, v37
	v_mov_b32_e32 v24, v49
	v_mov_b32_e32 v44, v73
	v_add_u32_e32 v111, 32, v111
	s_waitcnt vmcnt(23)
	v_pk_fma_f32 v[8:9], v[174:175], v[126:127], v[94:95] op_sel_hi:[0,1,1]
	v_pk_fma_f32 v[36:37], v[174:175], v[128:129], v[92:93] op_sel_hi:[0,1,1]
	v_pk_fma_f32 v[48:49], v[174:175], v[130:131], v[90:91] op_sel_hi:[0,1,1]
	v_pk_fma_f32 v[72:73], v[174:175], v[132:133], v[88:89] op_sel_hi:[0,1,1]
	s_waitcnt lgkmcnt(1)
	v_fmac_f32_e32 v0, v174, v62
	s_waitcnt vmcnt(22)
	v_pk_fma_f32 v[2:3], v[174:175], v[2:3], v[8:9] op_sel:[1,0,0] op_sel_hi:[1,1,1]
	v_pk_fma_f32 v[8:9], v[174:175], v[26:27], v[36:37] op_sel:[1,0,0] op_sel_hi:[1,1,1]
	v_pk_fma_f32 v[26:27], v[174:175], v[30:31], v[48:49] op_sel:[1,0,0] op_sel_hi:[1,1,1]
	v_pk_fma_f32 v[30:31], v[174:175], v[58:59], v[72:73] op_sel:[1,0,0] op_sel_hi:[1,1,1]
	v_fmac_f32_e32 v0, v175, v63
	s_waitcnt vmcnt(21)
	v_pk_fma_f32 v[2:3], v[176:177], v[10:11], v[2:3] op_sel_hi:[0,1,1]
	v_pk_fma_f32 v[8:9], v[176:177], v[38:39], v[8:9] op_sel_hi:[0,1,1]
	v_pk_fma_f32 v[10:11], v[176:177], v[54:55], v[26:27] op_sel_hi:[0,1,1]
	v_pk_fma_f32 v[26:27], v[176:177], v[66:67], v[30:31] op_sel_hi:[0,1,1]
	v_fmac_f32_e32 v0, v176, v64
	s_waitcnt vmcnt(20)
	v_pk_fma_f32 v[2:3], v[176:177], v[4:5], v[2:3] op_sel:[1,0,0] op_sel_hi:[1,1,1]
	v_pk_fma_f32 v[4:5], v[176:177], v[28:29], v[8:9] op_sel:[1,0,0] op_sel_hi:[1,1,1]
	v_pk_fma_f32 v[8:9], v[176:177], v[32:33], v[10:11] op_sel:[1,0,0] op_sel_hi:[1,1,1]
	v_pk_fma_f32 v[10:11], v[176:177], v[60:61], v[26:27] op_sel:[1,0,0] op_sel_hi:[1,1,1]
	v_fmac_f32_e32 v0, v177, v65
	s_waitcnt vmcnt(19)
	v_pk_fma_f32 v[2:3], v[178:179], v[12:13], v[2:3] op_sel_hi:[0,1,1]
	v_pk_fma_f32 v[4:5], v[178:179], v[40:41], v[4:5] op_sel_hi:[0,1,1]
	v_pk_fma_f32 v[8:9], v[178:179], v[56:57], v[8:9] op_sel_hi:[0,1,1]
	v_pk_fma_f32 v[10:11], v[178:179], v[68:69], v[10:11] op_sel_hi:[0,1,1]
	s_waitcnt lgkmcnt(0)
	v_fmac_f32_e32 v0, v178, v50
	s_waitcnt vmcnt(18)
	v_pk_fma_f32 v[2:3], v[178:179], v[14:15], v[2:3] op_sel:[1,0,0] op_sel_hi:[1,1,1]
	v_pk_fma_f32 v[4:5], v[178:179], v[18:19], v[4:5] op_sel:[1,0,0] op_sel_hi:[1,1,1]
	v_pk_fma_f32 v[8:9], v[178:179], v[22:23], v[8:9] op_sel:[1,0,0] op_sel_hi:[1,1,1]
	v_pk_fma_f32 v[10:11], v[178:179], v[42:43], v[10:11] op_sel:[1,0,0] op_sel_hi:[1,1,1]
	v_fmac_f32_e32 v0, v179, v51
	s_waitcnt vmcnt(17)
	v_pk_fma_f32 v[2:3], v[180:181], v[6:7], v[2:3] op_sel_hi:[0,1,1]
	v_pk_fma_f32 v[4:5], v[180:181], v[34:35], v[4:5] op_sel_hi:[0,1,1]
	v_pk_fma_f32 v[6:7], v[180:181], v[46:47], v[8:9] op_sel_hi:[0,1,1]
	v_pk_fma_f32 v[8:9], v[180:181], v[70:71], v[10:11] op_sel_hi:[0,1,1]
	v_fmac_f32_e32 v0, v180, v52
	s_waitcnt vmcnt(16)
	v_pk_fma_f32 v[94:95], v[180:181], v[16:17], v[2:3] op_sel:[1,0,0] op_sel_hi:[1,1,1]
	v_pk_fma_f32 v[92:93], v[180:181], v[20:21], v[4:5] op_sel:[1,0,0] op_sel_hi:[1,1,1]
	v_pk_fma_f32 v[90:91], v[180:181], v[24:25], v[6:7] op_sel:[1,0,0] op_sel_hi:[1,1,1]
	v_pk_fma_f32 v[88:89], v[180:181], v[44:45], v[8:9] op_sel:[1,0,0] op_sel_hi:[1,1,1]
	v_fmac_f32_e32 v0, v181, v53
	ds_read_b128 v[10:13], v111
	ds_read_b128 v[6:9], v111 offset:16
	ds_read_b128 v[2:5], v111 offset:512
	ds_read_b128 v[14:17], v111 offset:528
	ds_read_b128 v[38:41], v111 offset:1024
	ds_read_b128 v[34:37], v111 offset:1040
	ds_read_b128 v[26:29], v111 offset:1536
	ds_read_b128 v[18:21], v111 offset:1552
	ds_read_b128 v[54:57], v111 offset:2048
	ds_read_b128 v[46:49], v111 offset:2064
	ds_read_b128 v[30:33], v111 offset:2560
	ds_read_b128 v[22:25], v111 offset:2576
	ds_read_b128 v[66:69], v111 offset:3072
	ds_read_b128 v[70:73], v111 offset:3088
	ds_read_b128 v[58:61], v111 offset:3584
	ds_read_b128 v[42:45], v111 offset:3600
	ds_read_b128 v[62:65], v111 offset:4096
	ds_read_b128 v[50:53], v111 offset:4112
	s_waitcnt lgkmcnt(14)
	v_mov_b32_e32 v126, v10
	v_mov_b32_e32 v127, v2
	s_waitcnt lgkmcnt(13)
	v_mov_b32_e32 v128, v38
	s_waitcnt lgkmcnt(11)
	v_mov_b32_e32 v129, v26
	s_waitcnt lgkmcnt(9)
	v_mov_b32_e32 v130, v54
	s_waitcnt lgkmcnt(7)
	v_mov_b32_e32 v131, v30
	s_waitcnt lgkmcnt(5)
	v_mov_b32_e32 v132, v66
	s_waitcnt lgkmcnt(3)
	v_mov_b32_e32 v133, v58
	v_mov_b32_e32 v2, v11
	v_mov_b32_e32 v26, v39
	v_mov_b32_e32 v30, v55
	v_mov_b32_e32 v58, v67
	v_mov_b32_e32 v10, v12
	v_mov_b32_e32 v11, v4
	v_mov_b32_e32 v38, v40
	v_mov_b32_e32 v39, v28
	v_mov_b32_e32 v54, v56
	v_mov_b32_e32 v55, v32
	v_mov_b32_e32 v66, v68
	v_mov_b32_e32 v67, v60
	v_mov_b32_e32 v4, v13
	v_mov_b32_e32 v28, v41
	v_mov_b32_e32 v32, v57
	v_mov_b32_e32 v60, v69
	v_mov_b32_e32 v12, v6
	v_mov_b32_e32 v13, v14
	v_mov_b32_e32 v40, v34
	v_mov_b32_e32 v41, v18
	v_mov_b32_e32 v56, v46
	v_mov_b32_e32 v57, v22
	v_mov_b32_e32 v68, v70
	s_waitcnt lgkmcnt(2)
	v_mov_b32_e32 v69, v42
	v_mov_b32_e32 v14, v7
	v_mov_b32_e32 v18, v35
	v_mov_b32_e32 v22, v47
	v_mov_b32_e32 v42, v71
	v_mov_b32_e32 v6, v8
	v_mov_b32_e32 v7, v16
	v_mov_b32_e32 v34, v36
	v_mov_b32_e32 v35, v20
	v_mov_b32_e32 v46, v48
	v_mov_b32_e32 v47, v24
	v_mov_b32_e32 v70, v72
	v_mov_b32_e32 v71, v44
	v_mov_b32_e32 v16, v9
	v_mov_b32_e32 v20, v37
	v_mov_b32_e32 v24, v49
	v_mov_b32_e32 v44, v73
	v_add_u32_e32 v111, 32, v111
	s_waitcnt vmcnt(15)
	v_pk_fma_f32 v[8:9], v[182:183], v[126:127], v[94:95] op_sel_hi:[0,1,1]
	v_pk_fma_f32 v[36:37], v[182:183], v[128:129], v[92:93] op_sel_hi:[0,1,1]
	v_pk_fma_f32 v[48:49], v[182:183], v[130:131], v[90:91] op_sel_hi:[0,1,1]
	v_pk_fma_f32 v[72:73], v[182:183], v[132:133], v[88:89] op_sel_hi:[0,1,1]
	s_waitcnt lgkmcnt(1)
	v_fmac_f32_e32 v0, v182, v62
	s_waitcnt vmcnt(14)
	v_pk_fma_f32 v[2:3], v[182:183], v[2:3], v[8:9] op_sel:[1,0,0] op_sel_hi:[1,1,1]
	v_pk_fma_f32 v[8:9], v[182:183], v[26:27], v[36:37] op_sel:[1,0,0] op_sel_hi:[1,1,1]
	v_pk_fma_f32 v[26:27], v[182:183], v[30:31], v[48:49] op_sel:[1,0,0] op_sel_hi:[1,1,1]
	v_pk_fma_f32 v[30:31], v[182:183], v[58:59], v[72:73] op_sel:[1,0,0] op_sel_hi:[1,1,1]
	v_fmac_f32_e32 v0, v183, v63
	s_waitcnt vmcnt(13)
	v_pk_fma_f32 v[2:3], v[184:185], v[10:11], v[2:3] op_sel_hi:[0,1,1]
	v_pk_fma_f32 v[8:9], v[184:185], v[38:39], v[8:9] op_sel_hi:[0,1,1]
	v_pk_fma_f32 v[10:11], v[184:185], v[54:55], v[26:27] op_sel_hi:[0,1,1]
	v_pk_fma_f32 v[26:27], v[184:185], v[66:67], v[30:31] op_sel_hi:[0,1,1]
	v_fmac_f32_e32 v0, v184, v64
	s_waitcnt vmcnt(12)
	v_pk_fma_f32 v[2:3], v[184:185], v[4:5], v[2:3] op_sel:[1,0,0] op_sel_hi:[1,1,1]
	v_pk_fma_f32 v[4:5], v[184:185], v[28:29], v[8:9] op_sel:[1,0,0] op_sel_hi:[1,1,1]
	v_pk_fma_f32 v[8:9], v[184:185], v[32:33], v[10:11] op_sel:[1,0,0] op_sel_hi:[1,1,1]
	v_pk_fma_f32 v[10:11], v[184:185], v[60:61], v[26:27] op_sel:[1,0,0] op_sel_hi:[1,1,1]
	v_fmac_f32_e32 v0, v185, v65
	s_waitcnt vmcnt(11)
	v_pk_fma_f32 v[2:3], v[186:187], v[12:13], v[2:3] op_sel_hi:[0,1,1]
	v_pk_fma_f32 v[4:5], v[186:187], v[40:41], v[4:5] op_sel_hi:[0,1,1]
	v_pk_fma_f32 v[8:9], v[186:187], v[56:57], v[8:9] op_sel_hi:[0,1,1]
	v_pk_fma_f32 v[10:11], v[186:187], v[68:69], v[10:11] op_sel_hi:[0,1,1]
	s_waitcnt lgkmcnt(0)
	v_fmac_f32_e32 v0, v186, v50
	s_waitcnt vmcnt(10)
	v_pk_fma_f32 v[2:3], v[186:187], v[14:15], v[2:3] op_sel:[1,0,0] op_sel_hi:[1,1,1]
	v_pk_fma_f32 v[4:5], v[186:187], v[18:19], v[4:5] op_sel:[1,0,0] op_sel_hi:[1,1,1]
	v_pk_fma_f32 v[8:9], v[186:187], v[22:23], v[8:9] op_sel:[1,0,0] op_sel_hi:[1,1,1]
	v_pk_fma_f32 v[10:11], v[186:187], v[42:43], v[10:11] op_sel:[1,0,0] op_sel_hi:[1,1,1]
	v_fmac_f32_e32 v0, v187, v51
	s_waitcnt vmcnt(9)
	v_pk_fma_f32 v[2:3], v[188:189], v[6:7], v[2:3] op_sel_hi:[0,1,1]
	v_pk_fma_f32 v[4:5], v[188:189], v[34:35], v[4:5] op_sel_hi:[0,1,1]
	v_pk_fma_f32 v[6:7], v[188:189], v[46:47], v[8:9] op_sel_hi:[0,1,1]
	v_pk_fma_f32 v[8:9], v[188:189], v[70:71], v[10:11] op_sel_hi:[0,1,1]
	v_fmac_f32_e32 v0, v188, v52
	s_waitcnt vmcnt(8)
	v_pk_fma_f32 v[94:95], v[188:189], v[16:17], v[2:3] op_sel:[1,0,0] op_sel_hi:[1,1,1]
	v_pk_fma_f32 v[92:93], v[188:189], v[20:21], v[4:5] op_sel:[1,0,0] op_sel_hi:[1,1,1]
	v_pk_fma_f32 v[90:91], v[188:189], v[24:25], v[6:7] op_sel:[1,0,0] op_sel_hi:[1,1,1]
	v_pk_fma_f32 v[88:89], v[188:189], v[44:45], v[8:9] op_sel:[1,0,0] op_sel_hi:[1,1,1]
	v_fmac_f32_e32 v0, v189, v53
	ds_read_b128 v[10:13], v111
	ds_read_b128 v[6:9], v111 offset:16
	ds_read_b128 v[2:5], v111 offset:512
	ds_read_b128 v[14:17], v111 offset:528
	ds_read_b128 v[38:41], v111 offset:1024
	ds_read_b128 v[34:37], v111 offset:1040
	ds_read_b128 v[26:29], v111 offset:1536
	ds_read_b128 v[18:21], v111 offset:1552
	ds_read_b128 v[54:57], v111 offset:2048
	ds_read_b128 v[46:49], v111 offset:2064
	ds_read_b128 v[30:33], v111 offset:2560
	ds_read_b128 v[22:25], v111 offset:2576
	ds_read_b128 v[66:69], v111 offset:3072
	ds_read_b128 v[70:73], v111 offset:3088
	ds_read_b128 v[58:61], v111 offset:3584
	ds_read_b128 v[42:45], v111 offset:3600
	ds_read_b128 v[62:65], v111 offset:4096
	ds_read_b128 v[50:53], v111 offset:4112
	s_waitcnt lgkmcnt(14)
	v_mov_b32_e32 v126, v10
	v_mov_b32_e32 v127, v2
	s_waitcnt lgkmcnt(13)
	v_mov_b32_e32 v128, v38
	s_waitcnt lgkmcnt(11)
	v_mov_b32_e32 v129, v26
	s_waitcnt lgkmcnt(9)
	v_mov_b32_e32 v130, v54
	s_waitcnt lgkmcnt(7)
	v_mov_b32_e32 v131, v30
	s_waitcnt lgkmcnt(5)
	v_mov_b32_e32 v132, v66
	s_waitcnt lgkmcnt(3)
	v_mov_b32_e32 v133, v58
	v_mov_b32_e32 v2, v11
	v_mov_b32_e32 v26, v39
	v_mov_b32_e32 v30, v55
	v_mov_b32_e32 v58, v67
	v_mov_b32_e32 v10, v12
	v_mov_b32_e32 v11, v4
	v_mov_b32_e32 v38, v40
	v_mov_b32_e32 v39, v28
	v_mov_b32_e32 v54, v56
	v_mov_b32_e32 v55, v32
	v_mov_b32_e32 v66, v68
	v_mov_b32_e32 v67, v60
	v_mov_b32_e32 v4, v13
	v_mov_b32_e32 v28, v41
	v_mov_b32_e32 v32, v57
	v_mov_b32_e32 v60, v69
	v_mov_b32_e32 v12, v6
	v_mov_b32_e32 v13, v14
	v_mov_b32_e32 v40, v34
	v_mov_b32_e32 v41, v18
	v_mov_b32_e32 v56, v46
	v_mov_b32_e32 v57, v22
	v_mov_b32_e32 v68, v70
	s_waitcnt lgkmcnt(2)
	v_mov_b32_e32 v69, v42
	v_mov_b32_e32 v14, v7
	v_mov_b32_e32 v18, v35
	v_mov_b32_e32 v22, v47
	v_mov_b32_e32 v42, v71
	v_mov_b32_e32 v6, v8
	v_mov_b32_e32 v7, v16
	v_mov_b32_e32 v34, v36
	v_mov_b32_e32 v35, v20
	v_mov_b32_e32 v46, v48
	v_mov_b32_e32 v47, v24
	v_mov_b32_e32 v70, v72
	v_mov_b32_e32 v71, v44
	v_mov_b32_e32 v16, v9
	v_mov_b32_e32 v20, v37
	v_mov_b32_e32 v24, v49
	v_mov_b32_e32 v44, v73
	v_add_u32_e32 v111, 32, v111
	s_waitcnt vmcnt(7)
	v_pk_fma_f32 v[8:9], v[190:191], v[126:127], v[94:95] op_sel_hi:[0,1,1]
	v_pk_fma_f32 v[36:37], v[190:191], v[128:129], v[92:93] op_sel_hi:[0,1,1]
	v_pk_fma_f32 v[48:49], v[190:191], v[130:131], v[90:91] op_sel_hi:[0,1,1]
	v_pk_fma_f32 v[72:73], v[190:191], v[132:133], v[88:89] op_sel_hi:[0,1,1]
	s_waitcnt lgkmcnt(1)
	v_fmac_f32_e32 v0, v190, v62
	s_waitcnt vmcnt(6)
	v_pk_fma_f32 v[2:3], v[190:191], v[2:3], v[8:9] op_sel:[1,0,0] op_sel_hi:[1,1,1]
	v_pk_fma_f32 v[8:9], v[190:191], v[26:27], v[36:37] op_sel:[1,0,0] op_sel_hi:[1,1,1]
	v_pk_fma_f32 v[26:27], v[190:191], v[30:31], v[48:49] op_sel:[1,0,0] op_sel_hi:[1,1,1]
	v_pk_fma_f32 v[30:31], v[190:191], v[58:59], v[72:73] op_sel:[1,0,0] op_sel_hi:[1,1,1]
	v_fmac_f32_e32 v0, v191, v63
	s_waitcnt vmcnt(5)
	v_pk_fma_f32 v[2:3], v[192:193], v[10:11], v[2:3] op_sel_hi:[0,1,1]
	v_pk_fma_f32 v[8:9], v[192:193], v[38:39], v[8:9] op_sel_hi:[0,1,1]
	v_pk_fma_f32 v[10:11], v[192:193], v[54:55], v[26:27] op_sel_hi:[0,1,1]
	v_pk_fma_f32 v[26:27], v[192:193], v[66:67], v[30:31] op_sel_hi:[0,1,1]
	v_fmac_f32_e32 v0, v192, v64
	s_waitcnt vmcnt(4)
	v_pk_fma_f32 v[2:3], v[192:193], v[4:5], v[2:3] op_sel:[1,0,0] op_sel_hi:[1,1,1]
	v_pk_fma_f32 v[4:5], v[192:193], v[28:29], v[8:9] op_sel:[1,0,0] op_sel_hi:[1,1,1]
	v_pk_fma_f32 v[8:9], v[192:193], v[32:33], v[10:11] op_sel:[1,0,0] op_sel_hi:[1,1,1]
	v_pk_fma_f32 v[10:11], v[192:193], v[60:61], v[26:27] op_sel:[1,0,0] op_sel_hi:[1,1,1]
	v_fmac_f32_e32 v0, v193, v65
	s_waitcnt vmcnt(3)
	v_pk_fma_f32 v[2:3], v[194:195], v[12:13], v[2:3] op_sel_hi:[0,1,1]
	v_pk_fma_f32 v[4:5], v[194:195], v[40:41], v[4:5] op_sel_hi:[0,1,1]
	v_pk_fma_f32 v[8:9], v[194:195], v[56:57], v[8:9] op_sel_hi:[0,1,1]
	v_pk_fma_f32 v[10:11], v[194:195], v[68:69], v[10:11] op_sel_hi:[0,1,1]
	s_waitcnt lgkmcnt(0)
	v_fmac_f32_e32 v0, v194, v50
	s_waitcnt vmcnt(2)
	v_pk_fma_f32 v[2:3], v[194:195], v[14:15], v[2:3] op_sel:[1,0,0] op_sel_hi:[1,1,1]
	v_pk_fma_f32 v[4:5], v[194:195], v[18:19], v[4:5] op_sel:[1,0,0] op_sel_hi:[1,1,1]
	v_pk_fma_f32 v[8:9], v[194:195], v[22:23], v[8:9] op_sel:[1,0,0] op_sel_hi:[1,1,1]
	v_pk_fma_f32 v[10:11], v[194:195], v[42:43], v[10:11] op_sel:[1,0,0] op_sel_hi:[1,1,1]
	v_fmac_f32_e32 v0, v195, v51
	s_waitcnt vmcnt(1)
	v_pk_fma_f32 v[2:3], v[196:197], v[6:7], v[2:3] op_sel_hi:[0,1,1]
	v_pk_fma_f32 v[4:5], v[196:197], v[34:35], v[4:5] op_sel_hi:[0,1,1]
	v_pk_fma_f32 v[6:7], v[196:197], v[46:47], v[8:9] op_sel_hi:[0,1,1]
	v_pk_fma_f32 v[8:9], v[196:197], v[70:71], v[10:11] op_sel_hi:[0,1,1]
	v_fmac_f32_e32 v0, v196, v52
	s_waitcnt vmcnt(0)
	v_pk_fma_f32 v[94:95], v[196:197], v[16:17], v[2:3] op_sel:[1,0,0] op_sel_hi:[1,1,1]
	v_pk_fma_f32 v[92:93], v[196:197], v[20:21], v[4:5] op_sel:[1,0,0] op_sel_hi:[1,1,1]
	v_pk_fma_f32 v[90:91], v[196:197], v[24:25], v[6:7] op_sel:[1,0,0] op_sel_hi:[1,1,1]
	v_pk_fma_f32 v[88:89], v[196:197], v[44:45], v[8:9] op_sel:[1,0,0] op_sel_hi:[1,1,1]
	v_fmac_f32_e32 v0, v197, v53
	s_add_i32 s0, s6, 23
	s_cmp_lt_u32 s0, 47
	s_cselect_b64 s[0:1], -1, 0
	s_and_b64 s[4:5], s[38:39], s[0:1]
	v_mov_b32_e32 v2, 0
	s_and_saveexec_b64 s[0:1], s[4:5]
	s_cbranch_execz .LBB0_319
	v_readlane_b32 s64, v252, 33
	v_readlane_b32 s68, v252, 37
	v_readlane_b32 s69, v252, 38
	v_readlane_b32 s65, v252, 34
	v_readlane_b32 s66, v252, 35
	v_lshl_add_u64 v[2:3], v[86:87], 2, s[68:69]
	global_load_dword v2, v[2:3], off
	v_readlane_b32 s67, v252, 36
	v_readlane_b32 s70, v252, 39
	v_readlane_b32 s71, v252, 40
	v_readlane_b32 s72, v252, 41
	v_readlane_b32 s73, v252, 42
	v_readlane_b32 s74, v252, 43
	v_readlane_b32 s75, v252, 44
	v_readlane_b32 s76, v252, 45
	v_readlane_b32 s77, v252, 46
	v_readlane_b32 s78, v252, 47
	v_readlane_b32 s79, v252, 48
	s_branch .LBB0_319
